# static priority raise (s_setprio 2) for the wave running the lean in-proj epilogue
# baseline (speedup 1.0000x reference)
.LBB0_220:
	s_cmp_gt_i32 s7, 0
	s_waitcnt vmcnt(6)
	s_cselect_b32 s8, -1, 2
	s_mul_i32 s9, s7, 0x6000
	s_waitcnt lgkmcnt(0)
	s_add_i32 s8, s8, s7
	v_add_u32_e32 v139, s9, v224
	v_add_u32_e32 v0, s9, v223
	s_mulk_i32 s8, 0x6000
	v_add_u32_e32 v154, v139, v228
	s_barrier
	v_lshl_add_u64 v[170:171], v[144:145], 0, s[2:3]
	v_add_u32_e32 v141, s8, v221
	v_lshl_add_u64 v[174:175], v[142:143], 0, s[2:3]
	v_add_u32_e32 v182, s8, v222
	v_add_u32_e32 v166, v0, v228
	ds_read_b128 v[146:149], v166
	ds_read_b128 v[150:153], v154
	ds_read_b128 v[154:157], v154 offset:2048
	v_lshl_add_u64 v[172:173], v[170:171], 0, s[88:89]
	v_lshl_add_u64 v[176:177], v[174:175], 0, s[88:89]
	v_add_u32_e32 v183, 0x4000, v182
	v_lshl_add_u64 v[178:179], v[170:171], 0, s[90:91]
	v_add_u32_e32 v184, 0x400, v141
	v_lshl_add_u64 v[180:181], v[170:171], 0, s[78:79]
	v_add_u32_e32 v185, 0x800, v141
	ds_read_b128 v[158:161], v166 offset:2048
	ds_read_b128 v[162:165], v166 offset:4096
	ds_read_b128 v[166:169], v166 offset:6144
	s_waitcnt lgkmcnt(3)
	s_setprio 1
	v_mfma_f32_32x32x16_bf16 v[114:129], v[146:149], v[150:153], v[114:129]
	v_mfma_f32_32x32x16_bf16 v[98:113], v[146:149], v[154:157], v[98:113]
	v_readfirstlane_b32 s8, v141
	s_mov_b32 m0, s8
	s_nop 0
	global_load_lds_dwordx4 v[172:173], off
	s_waitcnt lgkmcnt(2)
	v_mfma_f32_32x32x16_bf16 v[82:97], v[158:161], v[150:153], v[82:97]
	v_mfma_f32_32x32x16_bf16 v[66:81], v[158:161], v[154:157], v[66:81]
	v_readfirstlane_b32 s8, v184
	s_mov_b32 m0, s8
	s_nop 0
	global_load_lds_dwordx4 v[178:179], off
	s_waitcnt lgkmcnt(1)
	v_mfma_f32_32x32x16_bf16 v[50:65], v[162:165], v[150:153], v[50:65]
	v_mfma_f32_32x32x16_bf16 v[34:49], v[162:165], v[154:157], v[34:49]
	v_readfirstlane_b32 s8, v185
	s_mov_b32 m0, s8
	s_nop 0
	global_load_lds_dwordx4 v[180:181], off
	s_waitcnt lgkmcnt(0)
	v_mfma_f32_32x32x16_bf16 v[18:33], v[166:169], v[150:153], v[18:33]
	v_mfma_f32_32x32x16_bf16 v[2:17], v[166:169], v[154:157], v[2:17]
	s_setprio 0
	v_add_u32_e32 v0, v0, v229
	v_add_u32_e32 v139, v139, v229
	ds_read_b128 v[146:149], v0
	ds_read_b128 v[150:153], v139
	ds_read_b128 v[154:157], v139 offset:2048
	ds_read_b128 v[158:161], v0 offset:2048
	ds_read_b128 v[162:165], v0 offset:4096
	ds_read_b128 v[166:169], v0 offset:6144
	s_waitcnt lgkmcnt(3)
	s_setprio 1
	v_mfma_f32_32x32x16_bf16 v[114:129], v[146:149], v[150:153], v[114:129]
	v_mfma_f32_32x32x16_bf16 v[98:113], v[146:149], v[154:157], v[98:113]
	v_add_u32_e32 v0, 0xc00, v141
	v_lshl_add_u64 v[146:147], v[170:171], 0, s[76:77]
	v_readfirstlane_b32 s8, v0
	s_mov_b32 m0, s8
	s_nop 0
	global_load_lds_dwordx4 v[146:147], off
	s_waitcnt lgkmcnt(2)
	v_mfma_f32_32x32x16_bf16 v[82:97], v[158:161], v[150:153], v[82:97]
	v_mfma_f32_32x32x16_bf16 v[66:81], v[158:161], v[154:157], v[66:81]
	v_readfirstlane_b32 s8, v183
	s_mov_b32 m0, s8
	s_nop 0
	global_load_lds_dwordx4 v[176:177], off
	s_waitcnt lgkmcnt(1)
	v_mfma_f32_32x32x16_bf16 v[50:65], v[162:165], v[150:153], v[50:65]
	v_mfma_f32_32x32x16_bf16 v[34:49], v[162:165], v[154:157], v[34:49]
	v_add_u32_e32 v0, 0x4400, v182
	v_lshl_add_u64 v[146:147], v[174:175], 0, s[90:91]
	v_readfirstlane_b32 s8, v0
	s_mov_b32 m0, s8
	s_nop 0
	global_load_lds_dwordx4 v[146:147], off
	s_waitcnt lgkmcnt(0)
	v_mfma_f32_32x32x16_bf16 v[18:33], v[166:169], v[150:153], v[18:33]
	v_mfma_f32_32x32x16_bf16 v[2:17], v[166:169], v[154:157], v[2:17]
	s_setprio 0
	s_add_i32 s8, s7, 1
	s_cmp_lt_i32 s7, 2
	s_cselect_b32 s7, s8, 0
	s_add_u32 s2, s2, 0x80
	s_addc_u32 s3, s3, 0
	s_cmpk_eq_i32 s2, 0xf00
	s_cbranch_scc0 .LBB0_220
	s_waitcnt vmcnt(6)
	s_mul_i32 s2, s7, 0x6000
	s_waitcnt lgkmcnt(0)
	v_add_u32_e32 v139, s2, v224
	v_add_u32_e32 v0, s2, v223
	v_add_u32_e32 v150, v139, v228
	s_barrier
	v_add_u32_e32 v141, v0, v228
	ds_read_b128 v[142:145], v141
	ds_read_b128 v[146:149], v150
	ds_read_b128 v[150:153], v150 offset:2048
	ds_read_b128 v[154:157], v141 offset:2048
	ds_read_b128 v[158:161], v141 offset:4096
	ds_read_b128 v[162:165], v141 offset:6144
	s_waitcnt lgkmcnt(3)
	s_setprio 1
	v_mfma_f32_32x32x16_bf16 v[114:129], v[142:145], v[146:149], v[114:129]
	v_mfma_f32_32x32x16_bf16 v[98:113], v[142:145], v[150:153], v[98:113]
	s_waitcnt lgkmcnt(2)
	v_mfma_f32_32x32x16_bf16 v[82:97], v[154:157], v[146:149], v[82:97]
	v_mfma_f32_32x32x16_bf16 v[66:81], v[154:157], v[150:153], v[66:81]
	s_waitcnt lgkmcnt(1)
	v_mfma_f32_32x32x16_bf16 v[50:65], v[158:161], v[146:149], v[50:65]
	v_mfma_f32_32x32x16_bf16 v[34:49], v[158:161], v[150:153], v[34:49]
	s_waitcnt lgkmcnt(0)
	v_mfma_f32_32x32x16_bf16 v[18:33], v[162:165], v[146:149], v[18:33]
	v_mfma_f32_32x32x16_bf16 v[2:17], v[162:165], v[150:153], v[2:17]
	s_setprio 0
	v_add_u32_e32 v0, v0, v229
	v_add_u32_e32 v139, v139, v229
	ds_read_b128 v[142:145], v0
	ds_read_b128 v[146:149], v139
	ds_read_b128 v[150:153], v139 offset:2048
	ds_read_b128 v[154:157], v0 offset:2048
	ds_read_b128 v[158:161], v0 offset:4096
	ds_read_b128 v[162:165], v0 offset:6144
	s_waitcnt lgkmcnt(3)
	s_setprio 1
	v_mfma_f32_32x32x16_bf16 v[114:129], v[142:145], v[146:149], v[114:129]
	v_mfma_f32_32x32x16_bf16 v[98:113], v[142:145], v[150:153], v[98:113]
	s_waitcnt lgkmcnt(2)
	v_mfma_f32_32x32x16_bf16 v[82:97], v[154:157], v[146:149], v[82:97]
	v_mfma_f32_32x32x16_bf16 v[66:81], v[154:157], v[150:153], v[66:81]
	s_waitcnt lgkmcnt(1)
	v_mfma_f32_32x32x16_bf16 v[50:65], v[158:161], v[146:149], v[50:65]
	v_mfma_f32_32x32x16_bf16 v[34:49], v[158:161], v[150:153], v[34:49]
	s_waitcnt lgkmcnt(0)
	v_mfma_f32_32x32x16_bf16 v[18:33], v[162:165], v[146:149], v[18:33]
	v_mfma_f32_32x32x16_bf16 v[2:17], v[162:165], v[150:153], v[2:17]
	s_setprio 0
	s_waitcnt vmcnt(0)
	s_waitcnt lgkmcnt(0)
	s_barrier
	ds_read_b128 v[142:145], v232
	ds_read_b128 v[146:149], v233
	ds_read_b128 v[150:153], v233 offset:2048
	ds_read_b128 v[154:157], v232 offset:2048
	ds_read_b128 v[158:161], v232 offset:4096
	ds_read_b128 v[162:165], v232 offset:6144
	s_waitcnt lgkmcnt(3)
	s_setprio 1
	v_mfma_f32_32x32x16_bf16 v[114:129], v[142:145], v[146:149], v[114:129]
	v_mfma_f32_32x32x16_bf16 v[98:113], v[142:145], v[150:153], v[98:113]
	s_waitcnt lgkmcnt(2)
	v_mfma_f32_32x32x16_bf16 v[82:97], v[154:157], v[146:149], v[82:97]
	v_mfma_f32_32x32x16_bf16 v[66:81], v[154:157], v[150:153], v[66:81]
	s_waitcnt lgkmcnt(1)
	v_mfma_f32_32x32x16_bf16 v[50:65], v[158:161], v[146:149], v[50:65]
	v_mfma_f32_32x32x16_bf16 v[34:49], v[158:161], v[150:153], v[34:49]
	s_waitcnt lgkmcnt(0)
	v_mfma_f32_32x32x16_bf16 v[18:33], v[162:165], v[146:149], v[18:33]
	v_mfma_f32_32x32x16_bf16 v[2:17], v[162:165], v[150:153], v[2:17]
	s_setprio 0
	ds_read_b128 v[142:145], v234
	ds_read_b128 v[146:149], v235
	ds_read_b128 v[150:153], v235 offset:2048
	ds_read_b128 v[154:157], v234 offset:2048
	ds_read_b128 v[158:161], v234 offset:4096
	ds_read_b128 v[162:165], v234 offset:6144
	s_waitcnt lgkmcnt(3)
	s_setprio 1
	v_mfma_f32_32x32x16_bf16 v[114:129], v[142:145], v[146:149], v[114:129]
	v_mfma_f32_32x32x16_bf16 v[98:113], v[142:145], v[150:153], v[98:113]
	s_waitcnt lgkmcnt(2)
	v_mfma_f32_32x32x16_bf16 v[82:97], v[154:157], v[146:149], v[82:97]
	v_mfma_f32_32x32x16_bf16 v[66:81], v[154:157], v[150:153], v[66:81]
	s_waitcnt lgkmcnt(1)
	v_mfma_f32_32x32x16_bf16 v[50:65], v[158:161], v[146:149], v[50:65]
	v_mfma_f32_32x32x16_bf16 v[34:49], v[158:161], v[150:153], v[34:49]
	s_waitcnt lgkmcnt(0)
	v_mfma_f32_32x32x16_bf16 v[18:33], v[162:165], v[146:149], v[18:33]
	v_mfma_f32_32x32x16_bf16 v[2:17], v[162:165], v[150:153], v[2:17]
	s_setprio 0
	s_cmp_gt_i32 s4, 3
	s_cselect_b64 s[30:31], -1, 0
	s_add_i32 s2, s4, -8
	s_cmp_gt_u32 s2, 5
	s_cselect_b64 s[98:99], -1, 0
	s_and_b32 s2, s4, 0x7ffffffc
	s_cmp_lg_u32 s2, 20
	v_add_u32_e32 v238, s5, v225
	s_cselect_b64 s[2:3], -1, 0
	s_and_b32 s5, s4, 0x7ffffffe
	s_cmp_eq_u32 s5, 6
	s_cselect_b64 s[82:83], -1, 0
	s_sub_i32 s5, s4, 17
	v_add_u32_e32 v239, 0x800, v230
	v_add_u32_e32 v240, 0x1000, v230
	v_add_u32_e32 v241, 0x1800, v230
	s_mov_b32 s8, 0x0701c030
	s_mov_b32 s34, 0x380e00c0
	s_lshr_b32 s8, s8, s4
	s_lshr_b32 s34, s34, s4
	s_and_b32 s8, s8, 1
	s_and_b32 s34, s34, 1
	s_or_b32 s7, s8, s34
	s_cmp_eq_u32 s7, 0
	s_cbranch_scc1 .Lmy_g0e_std
	s_setprio 2
	v_and_b32_e32 v151, 63, v200
	v_lshrrev_b32_e32 v150, 5, v151
	v_and_b32_e32 v146, 31, v151
	v_lshrrev_b32_e32 v147, 6, v200
	v_lshrrev_b32_e32 v152, 1, v147
	v_and_b32_e32 v148, 1, v147
	v_mul_u32_u24_e32 v147, 0x2200, v147
	s_movk_i32 s6, 0x7c00
	v_mad_u32_u24 v147, v152, s6, v147
	v_lshlrev_b32_e32 v146, 2, v146
	s_movk_i32 s6, 0x440
	v_mad_u32_u24 v146, v150, s6, v146
	v_add_u32_e32 v146, v146, v147
	v_lshrrev_b32_e32 v150, 3, v151
	v_and_b32_e32 v149, 7, v151
	s_movk_i32 s6, 0x110
	v_mad_u32_u24 v147, v150, s6, v147
	v_lshl_add_u32 v147, v149, 5, v147
	v_lshl_add_u32 v152, v152, 7, s32
	v_add_u32_e32 v152, v152, v150
	s_lshl_b32 s6, s4, 7
	v_lshl_add_u32 v148, v148, 6, s6
	v_lshl_add_u32 v148, v149, 3, v148
	v_lshlrev_b32_e32 v148, 1, v148
	v_mul_u32_u24_e32 v152, 0x1e00, v152
	v_add_u32_e32 v148, v148, v152
	s_mov_b64 s[8:9], s[64:65]
	s_cmp_eq_u32 s34, 1
	s_cbranch_scc1 .Lmy_g0e_gate
	ds_write2_b32 v146, v114, v98 offset0:0 offset1:32
	ds_write2_b32 v146, v115, v99 offset0:68 offset1:100
	ds_write2_b32 v146, v116, v100 offset0:136 offset1:168
	ds_write2_b32 v146, v117, v101 offset0:204 offset1:236
	v_add_u32_e32 v146, 0x880, v146
	ds_write2_b32 v146, v118, v102 offset0:0 offset1:32
	ds_write2_b32 v146, v119, v103 offset0:68 offset1:100
	ds_write2_b32 v146, v120, v104 offset0:136 offset1:168
	ds_write2_b32 v146, v121, v105 offset0:204 offset1:236
	v_add_u32_e32 v146, 0x880, v146
	ds_write2_b32 v146, v122, v106 offset0:0 offset1:32
	ds_write2_b32 v146, v123, v107 offset0:68 offset1:100
	ds_write2_b32 v146, v124, v108 offset0:136 offset1:168
	ds_write2_b32 v146, v125, v109 offset0:204 offset1:236
	v_add_u32_e32 v146, 0x880, v146
	ds_write2_b32 v146, v126, v110 offset0:0 offset1:32
	ds_write2_b32 v146, v127, v111 offset0:68 offset1:100
	ds_write2_b32 v146, v128, v112 offset0:136 offset1:168
	ds_write2_b32 v146, v129, v113 offset0:204 offset1:236
	v_subrev_u32_e32 v146, 0x1980, v146
	ds_read_b128 v[98:101], v147
	ds_read_b128 v[102:105], v147 offset:16
	ds_read_b128 v[106:109], v147 offset:2176
	ds_read_b128 v[110:113], v147 offset:2192
	ds_read_b128 v[114:117], v147 offset:4352
	ds_read_b128 v[118:121], v147 offset:4368
	ds_read_b128 v[122:125], v147 offset:6528
	ds_read_b128 v[126:129], v147 offset:6544
	s_waitcnt lgkmcnt(6)
	v_cvt_pk_bf16_f32 v154, v98, v99
	v_cvt_pk_bf16_f32 v155, v100, v101
	v_cvt_pk_bf16_f32 v156, v102, v103
	v_cvt_pk_bf16_f32 v157, v104, v105
	global_store_dwordx4 v148, v[154:157], s[8:9]
	s_add_u32 s8, s8, 0xf000
	s_addc_u32 s9, s9, 0
	s_waitcnt lgkmcnt(4)
	v_cvt_pk_bf16_f32 v158, v106, v107
	v_cvt_pk_bf16_f32 v159, v108, v109
	v_cvt_pk_bf16_f32 v160, v110, v111
	v_cvt_pk_bf16_f32 v161, v112, v113
	global_store_dwordx4 v148, v[158:161], s[8:9]
	s_add_u32 s8, s8, 0xf000
	s_addc_u32 s9, s9, 0
	s_waitcnt lgkmcnt(2)
	v_cvt_pk_bf16_f32 v162, v114, v115
	v_cvt_pk_bf16_f32 v163, v116, v117
	v_cvt_pk_bf16_f32 v164, v118, v119
	v_cvt_pk_bf16_f32 v165, v120, v121
	global_store_dwordx4 v148, v[162:165], s[8:9]
	s_add_u32 s8, s8, 0xf000
	s_addc_u32 s9, s9, 0
	s_waitcnt lgkmcnt(0)
	v_cvt_pk_bf16_f32 v166, v122, v123
	v_cvt_pk_bf16_f32 v167, v124, v125
	v_cvt_pk_bf16_f32 v168, v126, v127
	v_cvt_pk_bf16_f32 v169, v128, v129
	global_store_dwordx4 v148, v[166:169], s[8:9]
	s_add_u32 s8, s8, 0xf000
	s_addc_u32 s9, s9, 0
	ds_write2_b32 v146, v82, v66 offset0:0 offset1:32
	ds_write2_b32 v146, v83, v67 offset0:68 offset1:100
	ds_write2_b32 v146, v84, v68 offset0:136 offset1:168
	ds_write2_b32 v146, v85, v69 offset0:204 offset1:236
	v_add_u32_e32 v146, 0x880, v146
	ds_write2_b32 v146, v86, v70 offset0:0 offset1:32
	ds_write2_b32 v146, v87, v71 offset0:68 offset1:100
	ds_write2_b32 v146, v88, v72 offset0:136 offset1:168
	ds_write2_b32 v146, v89, v73 offset0:204 offset1:236
	v_add_u32_e32 v146, 0x880, v146
	ds_write2_b32 v146, v90, v74 offset0:0 offset1:32
	ds_write2_b32 v146, v91, v75 offset0:68 offset1:100
	ds_write2_b32 v146, v92, v76 offset0:136 offset1:168
	ds_write2_b32 v146, v93, v77 offset0:204 offset1:236
	v_add_u32_e32 v146, 0x880, v146
	ds_write2_b32 v146, v94, v78 offset0:0 offset1:32
	ds_write2_b32 v146, v95, v79 offset0:68 offset1:100
	ds_write2_b32 v146, v96, v80 offset0:136 offset1:168
	ds_write2_b32 v146, v97, v81 offset0:204 offset1:236
	v_subrev_u32_e32 v146, 0x1980, v146
	ds_read_b128 v[66:69], v147
	ds_read_b128 v[70:73], v147 offset:16
	ds_read_b128 v[74:77], v147 offset:2176
	ds_read_b128 v[78:81], v147 offset:2192
	ds_read_b128 v[82:85], v147 offset:4352
	ds_read_b128 v[86:89], v147 offset:4368
	ds_read_b128 v[90:93], v147 offset:6528
	ds_read_b128 v[94:97], v147 offset:6544
	s_waitcnt lgkmcnt(6)
	v_cvt_pk_bf16_f32 v154, v66, v67
	v_cvt_pk_bf16_f32 v155, v68, v69
	v_cvt_pk_bf16_f32 v156, v70, v71
	v_cvt_pk_bf16_f32 v157, v72, v73
	global_store_dwordx4 v148, v[154:157], s[8:9]
	s_add_u32 s8, s8, 0xf000
	s_addc_u32 s9, s9, 0
	s_waitcnt lgkmcnt(4)
	v_cvt_pk_bf16_f32 v158, v74, v75
	v_cvt_pk_bf16_f32 v159, v76, v77
	v_cvt_pk_bf16_f32 v160, v78, v79
	v_cvt_pk_bf16_f32 v161, v80, v81
	global_store_dwordx4 v148, v[158:161], s[8:9]
	s_add_u32 s8, s8, 0xf000
	s_addc_u32 s9, s9, 0
	s_waitcnt lgkmcnt(2)
	v_cvt_pk_bf16_f32 v162, v82, v83
	v_cvt_pk_bf16_f32 v163, v84, v85
	v_cvt_pk_bf16_f32 v164, v86, v87
	v_cvt_pk_bf16_f32 v165, v88, v89
	global_store_dwordx4 v148, v[162:165], s[8:9]
	s_add_u32 s8, s8, 0xf000
	s_addc_u32 s9, s9, 0
	s_waitcnt lgkmcnt(0)
	v_cvt_pk_bf16_f32 v166, v90, v91
	v_cvt_pk_bf16_f32 v167, v92, v93
	v_cvt_pk_bf16_f32 v168, v94, v95
	v_cvt_pk_bf16_f32 v169, v96, v97
	global_store_dwordx4 v148, v[166:169], s[8:9]
	s_add_u32 s8, s8, 0xf000
	s_addc_u32 s9, s9, 0
	ds_write2_b32 v146, v50, v34 offset0:0 offset1:32
	ds_write2_b32 v146, v51, v35 offset0:68 offset1:100
	ds_write2_b32 v146, v52, v36 offset0:136 offset1:168
	ds_write2_b32 v146, v53, v37 offset0:204 offset1:236
	v_add_u32_e32 v146, 0x880, v146
	ds_write2_b32 v146, v54, v38 offset0:0 offset1:32
	ds_write2_b32 v146, v55, v39 offset0:68 offset1:100
	ds_write2_b32 v146, v56, v40 offset0:136 offset1:168
	ds_write2_b32 v146, v57, v41 offset0:204 offset1:236
	v_add_u32_e32 v146, 0x880, v146
	ds_write2_b32 v146, v58, v42 offset0:0 offset1:32
	ds_write2_b32 v146, v59, v43 offset0:68 offset1:100
	ds_write2_b32 v146, v60, v44 offset0:136 offset1:168
	ds_write2_b32 v146, v61, v45 offset0:204 offset1:236
	v_add_u32_e32 v146, 0x880, v146
	ds_write2_b32 v146, v62, v46 offset0:0 offset1:32
	ds_write2_b32 v146, v63, v47 offset0:68 offset1:100
	ds_write2_b32 v146, v64, v48 offset0:136 offset1:168
	ds_write2_b32 v146, v65, v49 offset0:204 offset1:236
	v_subrev_u32_e32 v146, 0x1980, v146
	ds_read_b128 v[34:37], v147
	ds_read_b128 v[38:41], v147 offset:16
	ds_read_b128 v[42:45], v147 offset:2176
	ds_read_b128 v[46:49], v147 offset:2192
	ds_read_b128 v[50:53], v147 offset:4352
	ds_read_b128 v[54:57], v147 offset:4368
	ds_read_b128 v[58:61], v147 offset:6528
	ds_read_b128 v[62:65], v147 offset:6544
	s_waitcnt lgkmcnt(6)
	v_cvt_pk_bf16_f32 v154, v34, v35
	v_cvt_pk_bf16_f32 v155, v36, v37
	v_cvt_pk_bf16_f32 v156, v38, v39
	v_cvt_pk_bf16_f32 v157, v40, v41
	global_store_dwordx4 v148, v[154:157], s[8:9]
	s_add_u32 s8, s8, 0xf000
	s_addc_u32 s9, s9, 0
	s_waitcnt lgkmcnt(4)
	v_cvt_pk_bf16_f32 v158, v42, v43
	v_cvt_pk_bf16_f32 v159, v44, v45
	v_cvt_pk_bf16_f32 v160, v46, v47
	v_cvt_pk_bf16_f32 v161, v48, v49
	global_store_dwordx4 v148, v[158:161], s[8:9]
	s_add_u32 s8, s8, 0xf000
	s_addc_u32 s9, s9, 0
	s_waitcnt lgkmcnt(2)
	v_cvt_pk_bf16_f32 v162, v50, v51
	v_cvt_pk_bf16_f32 v163, v52, v53
	v_cvt_pk_bf16_f32 v164, v54, v55
	v_cvt_pk_bf16_f32 v165, v56, v57
	global_store_dwordx4 v148, v[162:165], s[8:9]
	s_add_u32 s8, s8, 0xf000
	s_addc_u32 s9, s9, 0
	s_waitcnt lgkmcnt(0)
	v_cvt_pk_bf16_f32 v166, v58, v59
	v_cvt_pk_bf16_f32 v167, v60, v61
	v_cvt_pk_bf16_f32 v168, v62, v63
	v_cvt_pk_bf16_f32 v169, v64, v65
	global_store_dwordx4 v148, v[166:169], s[8:9]
	s_add_u32 s8, s8, 0xf000
	s_addc_u32 s9, s9, 0
	ds_write2_b32 v146, v18, v2 offset0:0 offset1:32
	ds_write2_b32 v146, v19, v3 offset0:68 offset1:100
	ds_write2_b32 v146, v20, v4 offset0:136 offset1:168
	ds_write2_b32 v146, v21, v5 offset0:204 offset1:236
	v_add_u32_e32 v146, 0x880, v146
	ds_write2_b32 v146, v22, v6 offset0:0 offset1:32
	ds_write2_b32 v146, v23, v7 offset0:68 offset1:100
	ds_write2_b32 v146, v24, v8 offset0:136 offset1:168
	ds_write2_b32 v146, v25, v9 offset0:204 offset1:236
	v_add_u32_e32 v146, 0x880, v146
	ds_write2_b32 v146, v26, v10 offset0:0 offset1:32
	ds_write2_b32 v146, v27, v11 offset0:68 offset1:100
	ds_write2_b32 v146, v28, v12 offset0:136 offset1:168
	ds_write2_b32 v146, v29, v13 offset0:204 offset1:236
	v_add_u32_e32 v146, 0x880, v146
	ds_write2_b32 v146, v30, v14 offset0:0 offset1:32
	ds_write2_b32 v146, v31, v15 offset0:68 offset1:100
	ds_write2_b32 v146, v32, v16 offset0:136 offset1:168
	ds_write2_b32 v146, v33, v17 offset0:204 offset1:236
	v_subrev_u32_e32 v146, 0x1980, v146
	ds_read_b128 v[2:5], v147
	ds_read_b128 v[6:9], v147 offset:16
	ds_read_b128 v[10:13], v147 offset:2176
	ds_read_b128 v[14:17], v147 offset:2192
	ds_read_b128 v[18:21], v147 offset:4352
	ds_read_b128 v[22:25], v147 offset:4368
	ds_read_b128 v[26:29], v147 offset:6528
	ds_read_b128 v[30:33], v147 offset:6544
	s_waitcnt lgkmcnt(0)
	s_barrier
	v_cvt_pk_bf16_f32 v154, v2, v3
	v_cvt_pk_bf16_f32 v155, v4, v5
	v_cvt_pk_bf16_f32 v156, v6, v7
	v_cvt_pk_bf16_f32 v157, v8, v9
	global_store_dwordx4 v148, v[154:157], s[8:9]
	s_add_u32 s8, s8, 0xf000
	s_addc_u32 s9, s9, 0
	v_cvt_pk_bf16_f32 v158, v10, v11
	v_cvt_pk_bf16_f32 v159, v12, v13
	v_cvt_pk_bf16_f32 v160, v14, v15
	v_cvt_pk_bf16_f32 v161, v16, v17
	global_store_dwordx4 v148, v[158:161], s[8:9]
	s_add_u32 s8, s8, 0xf000
	s_addc_u32 s9, s9, 0
	v_cvt_pk_bf16_f32 v162, v18, v19
	v_cvt_pk_bf16_f32 v163, v20, v21
	v_cvt_pk_bf16_f32 v164, v22, v23
	v_cvt_pk_bf16_f32 v165, v24, v25
	global_store_dwordx4 v148, v[162:165], s[8:9]
	s_add_u32 s8, s8, 0xf000
	s_addc_u32 s9, s9, 0
	v_cvt_pk_bf16_f32 v166, v26, v27
	v_cvt_pk_bf16_f32 v167, v28, v29
	v_cvt_pk_bf16_f32 v168, v30, v31
	v_cvt_pk_bf16_f32 v169, v32, v33
	global_store_dwordx4 v148, v[166:169], s[8:9]
	s_add_u32 s8, s8, 0xf000
	s_addc_u32 s9, s9, 0
	s_add_i32 s70, s70, s10
	s_setprio 0
	s_cmp_lt_i32 s70, s71
	s_cbranch_scc0 .LBB0_209
	s_branch .LBB0_215
.Lmy_g0e_gate:
	ds_write2_b32 v146, v114, v98 offset0:0 offset1:32
	ds_write2_b32 v146, v115, v99 offset0:68 offset1:100
	ds_write2_b32 v146, v116, v100 offset0:136 offset1:168
	ds_write2_b32 v146, v117, v101 offset0:204 offset1:236
	v_add_u32_e32 v146, 0x880, v146
	ds_write2_b32 v146, v118, v102 offset0:0 offset1:32
	ds_write2_b32 v146, v119, v103 offset0:68 offset1:100
	ds_write2_b32 v146, v120, v104 offset0:136 offset1:168
	ds_write2_b32 v146, v121, v105 offset0:204 offset1:236
	v_add_u32_e32 v146, 0x880, v146
	ds_write2_b32 v146, v122, v106 offset0:0 offset1:32
	ds_write2_b32 v146, v123, v107 offset0:68 offset1:100
	ds_write2_b32 v146, v124, v108 offset0:136 offset1:168
	ds_write2_b32 v146, v125, v109 offset0:204 offset1:236
	v_add_u32_e32 v146, 0x880, v146
	ds_write2_b32 v146, v126, v110 offset0:0 offset1:32
	ds_write2_b32 v146, v127, v111 offset0:68 offset1:100
	ds_write2_b32 v146, v128, v112 offset0:136 offset1:168
	ds_write2_b32 v146, v129, v113 offset0:204 offset1:236
	v_subrev_u32_e32 v146, 0x1980, v146
	ds_read_b128 v[98:101], v147
	ds_read_b128 v[102:105], v147 offset:16
	ds_read_b128 v[106:109], v147 offset:2176
	ds_read_b128 v[110:113], v147 offset:2192
	ds_read_b128 v[114:117], v147 offset:4352
	ds_read_b128 v[118:121], v147 offset:4368
	ds_read_b128 v[122:125], v147 offset:6528
	ds_read_b128 v[126:129], v147 offset:6544
	s_waitcnt lgkmcnt(6)
	v_mul_f32_e32 v170, 0xbfb8aa3b, v98
	v_mul_f32_e32 v171, 0xbfb8aa3b, v99
	v_mul_f32_e32 v172, 0xbfb8aa3b, v100
	v_mul_f32_e32 v173, 0xbfb8aa3b, v101
	v_exp_f32_e32 v170, v170
	v_exp_f32_e32 v171, v171
	v_exp_f32_e32 v172, v172
	v_exp_f32_e32 v173, v173
	v_add_f32_e32 v170, 1.0, v170
	v_add_f32_e32 v171, 1.0, v171
	v_add_f32_e32 v172, 1.0, v172
	v_add_f32_e32 v173, 1.0, v173
	v_rcp_f32_e32 v170, v170
	v_rcp_f32_e32 v171, v171
	v_rcp_f32_e32 v172, v172
	v_rcp_f32_e32 v173, v173
	s_nop 0
	v_mul_f32_e32 v98, v98, v170
	v_mul_f32_e32 v99, v99, v171
	v_mul_f32_e32 v100, v100, v172
	v_mul_f32_e32 v101, v101, v173
	v_cvt_pk_bf16_f32 v154, v98, v99
	v_cvt_pk_bf16_f32 v155, v100, v101
	v_mul_f32_e32 v170, 0xbfb8aa3b, v102
	v_mul_f32_e32 v171, 0xbfb8aa3b, v103
	v_mul_f32_e32 v172, 0xbfb8aa3b, v104
	v_mul_f32_e32 v173, 0xbfb8aa3b, v105
	v_exp_f32_e32 v170, v170
	v_exp_f32_e32 v171, v171
	v_exp_f32_e32 v172, v172
	v_exp_f32_e32 v173, v173
	v_add_f32_e32 v170, 1.0, v170
	v_add_f32_e32 v171, 1.0, v171
	v_add_f32_e32 v172, 1.0, v172
	v_add_f32_e32 v173, 1.0, v173
	v_rcp_f32_e32 v170, v170
	v_rcp_f32_e32 v171, v171
	v_rcp_f32_e32 v172, v172
	v_rcp_f32_e32 v173, v173
	s_nop 0
	v_mul_f32_e32 v102, v102, v170
	v_mul_f32_e32 v103, v103, v171
	v_mul_f32_e32 v104, v104, v172
	v_mul_f32_e32 v105, v105, v173
	v_cvt_pk_bf16_f32 v156, v102, v103
	v_cvt_pk_bf16_f32 v157, v104, v105
	global_store_dwordx4 v148, v[154:157], s[8:9]
	s_add_u32 s8, s8, 0xf000
	s_addc_u32 s9, s9, 0
	s_waitcnt lgkmcnt(4)
	v_mul_f32_e32 v170, 0xbfb8aa3b, v106
	v_mul_f32_e32 v171, 0xbfb8aa3b, v107
	v_mul_f32_e32 v172, 0xbfb8aa3b, v108
	v_mul_f32_e32 v173, 0xbfb8aa3b, v109
	v_exp_f32_e32 v170, v170
	v_exp_f32_e32 v171, v171
	v_exp_f32_e32 v172, v172
	v_exp_f32_e32 v173, v173
	v_add_f32_e32 v170, 1.0, v170
	v_add_f32_e32 v171, 1.0, v171
	v_add_f32_e32 v172, 1.0, v172
	v_add_f32_e32 v173, 1.0, v173
	v_rcp_f32_e32 v170, v170
	v_rcp_f32_e32 v171, v171
	v_rcp_f32_e32 v172, v172
	v_rcp_f32_e32 v173, v173
	s_nop 0
	v_mul_f32_e32 v106, v106, v170
	v_mul_f32_e32 v107, v107, v171
	v_mul_f32_e32 v108, v108, v172
	v_mul_f32_e32 v109, v109, v173
	v_cvt_pk_bf16_f32 v158, v106, v107
	v_cvt_pk_bf16_f32 v159, v108, v109
	v_mul_f32_e32 v170, 0xbfb8aa3b, v110
	v_mul_f32_e32 v171, 0xbfb8aa3b, v111
	v_mul_f32_e32 v172, 0xbfb8aa3b, v112
	v_mul_f32_e32 v173, 0xbfb8aa3b, v113
	v_exp_f32_e32 v170, v170
	v_exp_f32_e32 v171, v171
	v_exp_f32_e32 v172, v172
	v_exp_f32_e32 v173, v173
	v_add_f32_e32 v170, 1.0, v170
	v_add_f32_e32 v171, 1.0, v171
	v_add_f32_e32 v172, 1.0, v172
	v_add_f32_e32 v173, 1.0, v173
	v_rcp_f32_e32 v170, v170
	v_rcp_f32_e32 v171, v171
	v_rcp_f32_e32 v172, v172
	v_rcp_f32_e32 v173, v173
	s_nop 0
	v_mul_f32_e32 v110, v110, v170
	v_mul_f32_e32 v111, v111, v171
	v_mul_f32_e32 v112, v112, v172
	v_mul_f32_e32 v113, v113, v173
	v_cvt_pk_bf16_f32 v160, v110, v111
	v_cvt_pk_bf16_f32 v161, v112, v113
	global_store_dwordx4 v148, v[158:161], s[8:9]
	s_add_u32 s8, s8, 0xf000
	s_addc_u32 s9, s9, 0
	s_waitcnt lgkmcnt(2)
	v_mul_f32_e32 v170, 0xbfb8aa3b, v114
	v_mul_f32_e32 v171, 0xbfb8aa3b, v115
	v_mul_f32_e32 v172, 0xbfb8aa3b, v116
	v_mul_f32_e32 v173, 0xbfb8aa3b, v117
	v_exp_f32_e32 v170, v170
	v_exp_f32_e32 v171, v171
	v_exp_f32_e32 v172, v172
	v_exp_f32_e32 v173, v173
	v_add_f32_e32 v170, 1.0, v170
	v_add_f32_e32 v171, 1.0, v171
	v_add_f32_e32 v172, 1.0, v172
	v_add_f32_e32 v173, 1.0, v173
	v_rcp_f32_e32 v170, v170
	v_rcp_f32_e32 v171, v171
	v_rcp_f32_e32 v172, v172
	v_rcp_f32_e32 v173, v173
	s_nop 0
	v_mul_f32_e32 v114, v114, v170
	v_mul_f32_e32 v115, v115, v171
	v_mul_f32_e32 v116, v116, v172
	v_mul_f32_e32 v117, v117, v173
	v_cvt_pk_bf16_f32 v162, v114, v115
	v_cvt_pk_bf16_f32 v163, v116, v117
	v_mul_f32_e32 v170, 0xbfb8aa3b, v118
	v_mul_f32_e32 v171, 0xbfb8aa3b, v119
	v_mul_f32_e32 v172, 0xbfb8aa3b, v120
	v_mul_f32_e32 v173, 0xbfb8aa3b, v121
	v_exp_f32_e32 v170, v170
	v_exp_f32_e32 v171, v171
	v_exp_f32_e32 v172, v172
	v_exp_f32_e32 v173, v173
	v_add_f32_e32 v170, 1.0, v170
	v_add_f32_e32 v171, 1.0, v171
	v_add_f32_e32 v172, 1.0, v172
	v_add_f32_e32 v173, 1.0, v173
	v_rcp_f32_e32 v170, v170
	v_rcp_f32_e32 v171, v171
	v_rcp_f32_e32 v172, v172
	v_rcp_f32_e32 v173, v173
	s_nop 0
	v_mul_f32_e32 v118, v118, v170
	v_mul_f32_e32 v119, v119, v171
	v_mul_f32_e32 v120, v120, v172
	v_mul_f32_e32 v121, v121, v173
	v_cvt_pk_bf16_f32 v164, v118, v119
	v_cvt_pk_bf16_f32 v165, v120, v121
	global_store_dwordx4 v148, v[162:165], s[8:9]
	s_add_u32 s8, s8, 0xf000
	s_addc_u32 s9, s9, 0
	s_waitcnt lgkmcnt(0)
	v_mul_f32_e32 v170, 0xbfb8aa3b, v122
	v_mul_f32_e32 v171, 0xbfb8aa3b, v123
	v_mul_f32_e32 v172, 0xbfb8aa3b, v124
	v_mul_f32_e32 v173, 0xbfb8aa3b, v125
	v_exp_f32_e32 v170, v170
	v_exp_f32_e32 v171, v171
	v_exp_f32_e32 v172, v172
	v_exp_f32_e32 v173, v173
	v_add_f32_e32 v170, 1.0, v170
	v_add_f32_e32 v171, 1.0, v171
	v_add_f32_e32 v172, 1.0, v172
	v_add_f32_e32 v173, 1.0, v173
	v_rcp_f32_e32 v170, v170
	v_rcp_f32_e32 v171, v171
	v_rcp_f32_e32 v172, v172
	v_rcp_f32_e32 v173, v173
	s_nop 0
	v_mul_f32_e32 v122, v122, v170
	v_mul_f32_e32 v123, v123, v171
	v_mul_f32_e32 v124, v124, v172
	v_mul_f32_e32 v125, v125, v173
	v_cvt_pk_bf16_f32 v166, v122, v123
	v_cvt_pk_bf16_f32 v167, v124, v125
	v_mul_f32_e32 v170, 0xbfb8aa3b, v126
	v_mul_f32_e32 v171, 0xbfb8aa3b, v127
	v_mul_f32_e32 v172, 0xbfb8aa3b, v128
	v_mul_f32_e32 v173, 0xbfb8aa3b, v129
	v_exp_f32_e32 v170, v170
	v_exp_f32_e32 v171, v171
	v_exp_f32_e32 v172, v172
	v_exp_f32_e32 v173, v173
	v_add_f32_e32 v170, 1.0, v170
	v_add_f32_e32 v171, 1.0, v171
	v_add_f32_e32 v172, 1.0, v172
	v_add_f32_e32 v173, 1.0, v173
	v_rcp_f32_e32 v170, v170
	v_rcp_f32_e32 v171, v171
	v_rcp_f32_e32 v172, v172
	v_rcp_f32_e32 v173, v173
	s_nop 0
	v_mul_f32_e32 v126, v126, v170
	v_mul_f32_e32 v127, v127, v171
	v_mul_f32_e32 v128, v128, v172
	v_mul_f32_e32 v129, v129, v173
	v_cvt_pk_bf16_f32 v168, v126, v127
	v_cvt_pk_bf16_f32 v169, v128, v129
	global_store_dwordx4 v148, v[166:169], s[8:9]
	s_add_u32 s8, s8, 0xf000
	s_addc_u32 s9, s9, 0
	ds_write2_b32 v146, v82, v66 offset0:0 offset1:32
	ds_write2_b32 v146, v83, v67 offset0:68 offset1:100
	ds_write2_b32 v146, v84, v68 offset0:136 offset1:168
	ds_write2_b32 v146, v85, v69 offset0:204 offset1:236
	v_add_u32_e32 v146, 0x880, v146
	ds_write2_b32 v146, v86, v70 offset0:0 offset1:32
	ds_write2_b32 v146, v87, v71 offset0:68 offset1:100
	ds_write2_b32 v146, v88, v72 offset0:136 offset1:168
	ds_write2_b32 v146, v89, v73 offset0:204 offset1:236
	v_add_u32_e32 v146, 0x880, v146
	ds_write2_b32 v146, v90, v74 offset0:0 offset1:32
	ds_write2_b32 v146, v91, v75 offset0:68 offset1:100
	ds_write2_b32 v146, v92, v76 offset0:136 offset1:168
	ds_write2_b32 v146, v93, v77 offset0:204 offset1:236
	v_add_u32_e32 v146, 0x880, v146
	ds_write2_b32 v146, v94, v78 offset0:0 offset1:32
	ds_write2_b32 v146, v95, v79 offset0:68 offset1:100
	ds_write2_b32 v146, v96, v80 offset0:136 offset1:168
	ds_write2_b32 v146, v97, v81 offset0:204 offset1:236
	v_subrev_u32_e32 v146, 0x1980, v146
	ds_read_b128 v[66:69], v147
	ds_read_b128 v[70:73], v147 offset:16
	ds_read_b128 v[74:77], v147 offset:2176
	ds_read_b128 v[78:81], v147 offset:2192
	ds_read_b128 v[82:85], v147 offset:4352
	ds_read_b128 v[86:89], v147 offset:4368
	ds_read_b128 v[90:93], v147 offset:6528
	ds_read_b128 v[94:97], v147 offset:6544
	s_waitcnt lgkmcnt(6)
	v_mul_f32_e32 v170, 0xbfb8aa3b, v66
	v_mul_f32_e32 v171, 0xbfb8aa3b, v67
	v_mul_f32_e32 v172, 0xbfb8aa3b, v68
	v_mul_f32_e32 v173, 0xbfb8aa3b, v69
	v_exp_f32_e32 v170, v170
	v_exp_f32_e32 v171, v171
	v_exp_f32_e32 v172, v172
	v_exp_f32_e32 v173, v173
	v_add_f32_e32 v170, 1.0, v170
	v_add_f32_e32 v171, 1.0, v171
	v_add_f32_e32 v172, 1.0, v172
	v_add_f32_e32 v173, 1.0, v173
	v_rcp_f32_e32 v170, v170
	v_rcp_f32_e32 v171, v171
	v_rcp_f32_e32 v172, v172
	v_rcp_f32_e32 v173, v173
	s_nop 0
	v_mul_f32_e32 v66, v66, v170
	v_mul_f32_e32 v67, v67, v171
	v_mul_f32_e32 v68, v68, v172
	v_mul_f32_e32 v69, v69, v173
	v_cvt_pk_bf16_f32 v154, v66, v67
	v_cvt_pk_bf16_f32 v155, v68, v69
	v_mul_f32_e32 v170, 0xbfb8aa3b, v70
	v_mul_f32_e32 v171, 0xbfb8aa3b, v71
	v_mul_f32_e32 v172, 0xbfb8aa3b, v72
	v_mul_f32_e32 v173, 0xbfb8aa3b, v73
	v_exp_f32_e32 v170, v170
	v_exp_f32_e32 v171, v171
	v_exp_f32_e32 v172, v172
	v_exp_f32_e32 v173, v173
	v_add_f32_e32 v170, 1.0, v170
	v_add_f32_e32 v171, 1.0, v171
	v_add_f32_e32 v172, 1.0, v172
	v_add_f32_e32 v173, 1.0, v173
	v_rcp_f32_e32 v170, v170
	v_rcp_f32_e32 v171, v171
	v_rcp_f32_e32 v172, v172
	v_rcp_f32_e32 v173, v173
	s_nop 0
	v_mul_f32_e32 v70, v70, v170
	v_mul_f32_e32 v71, v71, v171
	v_mul_f32_e32 v72, v72, v172
	v_mul_f32_e32 v73, v73, v173
	v_cvt_pk_bf16_f32 v156, v70, v71
	v_cvt_pk_bf16_f32 v157, v72, v73
	global_store_dwordx4 v148, v[154:157], s[8:9]
	s_add_u32 s8, s8, 0xf000
	s_addc_u32 s9, s9, 0
	s_waitcnt lgkmcnt(4)
	v_mul_f32_e32 v170, 0xbfb8aa3b, v74
	v_mul_f32_e32 v171, 0xbfb8aa3b, v75
	v_mul_f32_e32 v172, 0xbfb8aa3b, v76
	v_mul_f32_e32 v173, 0xbfb8aa3b, v77
	v_exp_f32_e32 v170, v170
	v_exp_f32_e32 v171, v171
	v_exp_f32_e32 v172, v172
	v_exp_f32_e32 v173, v173
	v_add_f32_e32 v170, 1.0, v170
	v_add_f32_e32 v171, 1.0, v171
	v_add_f32_e32 v172, 1.0, v172
	v_add_f32_e32 v173, 1.0, v173
	v_rcp_f32_e32 v170, v170
	v_rcp_f32_e32 v171, v171
	v_rcp_f32_e32 v172, v172
	v_rcp_f32_e32 v173, v173
	s_nop 0
	v_mul_f32_e32 v74, v74, v170
	v_mul_f32_e32 v75, v75, v171
	v_mul_f32_e32 v76, v76, v172
	v_mul_f32_e32 v77, v77, v173
	v_cvt_pk_bf16_f32 v158, v74, v75
	v_cvt_pk_bf16_f32 v159, v76, v77
	v_mul_f32_e32 v170, 0xbfb8aa3b, v78
	v_mul_f32_e32 v171, 0xbfb8aa3b, v79
	v_mul_f32_e32 v172, 0xbfb8aa3b, v80
	v_mul_f32_e32 v173, 0xbfb8aa3b, v81
	v_exp_f32_e32 v170, v170
	v_exp_f32_e32 v171, v171
	v_exp_f32_e32 v172, v172
	v_exp_f32_e32 v173, v173
	v_add_f32_e32 v170, 1.0, v170
	v_add_f32_e32 v171, 1.0, v171
	v_add_f32_e32 v172, 1.0, v172
	v_add_f32_e32 v173, 1.0, v173
	v_rcp_f32_e32 v170, v170
	v_rcp_f32_e32 v171, v171
	v_rcp_f32_e32 v172, v172
	v_rcp_f32_e32 v173, v173
	s_nop 0
	v_mul_f32_e32 v78, v78, v170
	v_mul_f32_e32 v79, v79, v171
	v_mul_f32_e32 v80, v80, v172
	v_mul_f32_e32 v81, v81, v173
	v_cvt_pk_bf16_f32 v160, v78, v79
	v_cvt_pk_bf16_f32 v161, v80, v81
	global_store_dwordx4 v148, v[158:161], s[8:9]
	s_add_u32 s8, s8, 0xf000
	s_addc_u32 s9, s9, 0
	s_waitcnt lgkmcnt(2)
	v_mul_f32_e32 v170, 0xbfb8aa3b, v82
	v_mul_f32_e32 v171, 0xbfb8aa3b, v83
	v_mul_f32_e32 v172, 0xbfb8aa3b, v84
	v_mul_f32_e32 v173, 0xbfb8aa3b, v85
	v_exp_f32_e32 v170, v170
	v_exp_f32_e32 v171, v171
	v_exp_f32_e32 v172, v172
	v_exp_f32_e32 v173, v173
	v_add_f32_e32 v170, 1.0, v170
	v_add_f32_e32 v171, 1.0, v171
	v_add_f32_e32 v172, 1.0, v172
	v_add_f32_e32 v173, 1.0, v173
	v_rcp_f32_e32 v170, v170
	v_rcp_f32_e32 v171, v171
	v_rcp_f32_e32 v172, v172
	v_rcp_f32_e32 v173, v173
	s_nop 0
	v_mul_f32_e32 v82, v82, v170
	v_mul_f32_e32 v83, v83, v171
	v_mul_f32_e32 v84, v84, v172
	v_mul_f32_e32 v85, v85, v173
	v_cvt_pk_bf16_f32 v162, v82, v83
	v_cvt_pk_bf16_f32 v163, v84, v85
	v_mul_f32_e32 v170, 0xbfb8aa3b, v86
	v_mul_f32_e32 v171, 0xbfb8aa3b, v87
	v_mul_f32_e32 v172, 0xbfb8aa3b, v88
	v_mul_f32_e32 v173, 0xbfb8aa3b, v89
	v_exp_f32_e32 v170, v170
	v_exp_f32_e32 v171, v171
	v_exp_f32_e32 v172, v172
	v_exp_f32_e32 v173, v173
	v_add_f32_e32 v170, 1.0, v170
	v_add_f32_e32 v171, 1.0, v171
	v_add_f32_e32 v172, 1.0, v172
	v_add_f32_e32 v173, 1.0, v173
	v_rcp_f32_e32 v170, v170
	v_rcp_f32_e32 v171, v171
	v_rcp_f32_e32 v172, v172
	v_rcp_f32_e32 v173, v173
	s_nop 0
	v_mul_f32_e32 v86, v86, v170
	v_mul_f32_e32 v87, v87, v171
	v_mul_f32_e32 v88, v88, v172
	v_mul_f32_e32 v89, v89, v173
	v_cvt_pk_bf16_f32 v164, v86, v87
	v_cvt_pk_bf16_f32 v165, v88, v89
	global_store_dwordx4 v148, v[162:165], s[8:9]
	s_add_u32 s8, s8, 0xf000
	s_addc_u32 s9, s9, 0
	s_waitcnt lgkmcnt(0)
	v_mul_f32_e32 v170, 0xbfb8aa3b, v90
	v_mul_f32_e32 v171, 0xbfb8aa3b, v91
	v_mul_f32_e32 v172, 0xbfb8aa3b, v92
	v_mul_f32_e32 v173, 0xbfb8aa3b, v93
	v_exp_f32_e32 v170, v170
	v_exp_f32_e32 v171, v171
	v_exp_f32_e32 v172, v172
	v_exp_f32_e32 v173, v173
	v_add_f32_e32 v170, 1.0, v170
	v_add_f32_e32 v171, 1.0, v171
	v_add_f32_e32 v172, 1.0, v172
	v_add_f32_e32 v173, 1.0, v173
	v_rcp_f32_e32 v170, v170
	v_rcp_f32_e32 v171, v171
	v_rcp_f32_e32 v172, v172
	v_rcp_f32_e32 v173, v173
	s_nop 0
	v_mul_f32_e32 v90, v90, v170
	v_mul_f32_e32 v91, v91, v171
	v_mul_f32_e32 v92, v92, v172
	v_mul_f32_e32 v93, v93, v173
	v_cvt_pk_bf16_f32 v166, v90, v91
	v_cvt_pk_bf16_f32 v167, v92, v93
	v_mul_f32_e32 v170, 0xbfb8aa3b, v94
	v_mul_f32_e32 v171, 0xbfb8aa3b, v95
	v_mul_f32_e32 v172, 0xbfb8aa3b, v96
	v_mul_f32_e32 v173, 0xbfb8aa3b, v97
	v_exp_f32_e32 v170, v170
	v_exp_f32_e32 v171, v171
	v_exp_f32_e32 v172, v172
	v_exp_f32_e32 v173, v173
	v_add_f32_e32 v170, 1.0, v170
	v_add_f32_e32 v171, 1.0, v171
	v_add_f32_e32 v172, 1.0, v172
	v_add_f32_e32 v173, 1.0, v173
	v_rcp_f32_e32 v170, v170
	v_rcp_f32_e32 v171, v171
	v_rcp_f32_e32 v172, v172
	v_rcp_f32_e32 v173, v173
	s_nop 0
	v_mul_f32_e32 v94, v94, v170
	v_mul_f32_e32 v95, v95, v171
	v_mul_f32_e32 v96, v96, v172
	v_mul_f32_e32 v97, v97, v173
	v_cvt_pk_bf16_f32 v168, v94, v95
	v_cvt_pk_bf16_f32 v169, v96, v97
	global_store_dwordx4 v148, v[166:169], s[8:9]
	s_add_u32 s8, s8, 0xf000
	s_addc_u32 s9, s9, 0
	ds_write2_b32 v146, v50, v34 offset0:0 offset1:32
	ds_write2_b32 v146, v51, v35 offset0:68 offset1:100
	ds_write2_b32 v146, v52, v36 offset0:136 offset1:168
	ds_write2_b32 v146, v53, v37 offset0:204 offset1:236
	v_add_u32_e32 v146, 0x880, v146
	ds_write2_b32 v146, v54, v38 offset0:0 offset1:32
	ds_write2_b32 v146, v55, v39 offset0:68 offset1:100
	ds_write2_b32 v146, v56, v40 offset0:136 offset1:168
	ds_write2_b32 v146, v57, v41 offset0:204 offset1:236
	v_add_u32_e32 v146, 0x880, v146
	ds_write2_b32 v146, v58, v42 offset0:0 offset1:32
	ds_write2_b32 v146, v59, v43 offset0:68 offset1:100
	ds_write2_b32 v146, v60, v44 offset0:136 offset1:168
	ds_write2_b32 v146, v61, v45 offset0:204 offset1:236
	v_add_u32_e32 v146, 0x880, v146
	ds_write2_b32 v146, v62, v46 offset0:0 offset1:32
	ds_write2_b32 v146, v63, v47 offset0:68 offset1:100
	ds_write2_b32 v146, v64, v48 offset0:136 offset1:168
	ds_write2_b32 v146, v65, v49 offset0:204 offset1:236
	v_subrev_u32_e32 v146, 0x1980, v146
	ds_read_b128 v[34:37], v147
	ds_read_b128 v[38:41], v147 offset:16
	ds_read_b128 v[42:45], v147 offset:2176
	ds_read_b128 v[46:49], v147 offset:2192
	ds_read_b128 v[50:53], v147 offset:4352
	ds_read_b128 v[54:57], v147 offset:4368
	ds_read_b128 v[58:61], v147 offset:6528
	ds_read_b128 v[62:65], v147 offset:6544
	s_waitcnt lgkmcnt(6)
	v_mul_f32_e32 v170, 0xbfb8aa3b, v34
	v_mul_f32_e32 v171, 0xbfb8aa3b, v35
	v_mul_f32_e32 v172, 0xbfb8aa3b, v36
	v_mul_f32_e32 v173, 0xbfb8aa3b, v37
	v_exp_f32_e32 v170, v170
	v_exp_f32_e32 v171, v171
	v_exp_f32_e32 v172, v172
	v_exp_f32_e32 v173, v173
	v_add_f32_e32 v170, 1.0, v170
	v_add_f32_e32 v171, 1.0, v171
	v_add_f32_e32 v172, 1.0, v172
	v_add_f32_e32 v173, 1.0, v173
	v_rcp_f32_e32 v170, v170
	v_rcp_f32_e32 v171, v171
	v_rcp_f32_e32 v172, v172
	v_rcp_f32_e32 v173, v173
	s_nop 0
	v_mul_f32_e32 v34, v34, v170
	v_mul_f32_e32 v35, v35, v171
	v_mul_f32_e32 v36, v36, v172
	v_mul_f32_e32 v37, v37, v173
	v_cvt_pk_bf16_f32 v154, v34, v35
	v_cvt_pk_bf16_f32 v155, v36, v37
	v_mul_f32_e32 v170, 0xbfb8aa3b, v38
	v_mul_f32_e32 v171, 0xbfb8aa3b, v39
	v_mul_f32_e32 v172, 0xbfb8aa3b, v40
	v_mul_f32_e32 v173, 0xbfb8aa3b, v41
	v_exp_f32_e32 v170, v170
	v_exp_f32_e32 v171, v171
	v_exp_f32_e32 v172, v172
	v_exp_f32_e32 v173, v173
	v_add_f32_e32 v170, 1.0, v170
	v_add_f32_e32 v171, 1.0, v171
	v_add_f32_e32 v172, 1.0, v172
	v_add_f32_e32 v173, 1.0, v173
	v_rcp_f32_e32 v170, v170
	v_rcp_f32_e32 v171, v171
	v_rcp_f32_e32 v172, v172
	v_rcp_f32_e32 v173, v173
	s_nop 0
	v_mul_f32_e32 v38, v38, v170
	v_mul_f32_e32 v39, v39, v171
	v_mul_f32_e32 v40, v40, v172
	v_mul_f32_e32 v41, v41, v173
	v_cvt_pk_bf16_f32 v156, v38, v39
	v_cvt_pk_bf16_f32 v157, v40, v41
	global_store_dwordx4 v148, v[154:157], s[8:9]
	s_add_u32 s8, s8, 0xf000
	s_addc_u32 s9, s9, 0
	s_waitcnt lgkmcnt(4)
	v_mul_f32_e32 v170, 0xbfb8aa3b, v42
	v_mul_f32_e32 v171, 0xbfb8aa3b, v43
	v_mul_f32_e32 v172, 0xbfb8aa3b, v44
	v_mul_f32_e32 v173, 0xbfb8aa3b, v45
	v_exp_f32_e32 v170, v170
	v_exp_f32_e32 v171, v171
	v_exp_f32_e32 v172, v172
	v_exp_f32_e32 v173, v173
	v_add_f32_e32 v170, 1.0, v170
	v_add_f32_e32 v171, 1.0, v171
	v_add_f32_e32 v172, 1.0, v172
	v_add_f32_e32 v173, 1.0, v173
	v_rcp_f32_e32 v170, v170
	v_rcp_f32_e32 v171, v171
	v_rcp_f32_e32 v172, v172
	v_rcp_f32_e32 v173, v173
	s_nop 0
	v_mul_f32_e32 v42, v42, v170
	v_mul_f32_e32 v43, v43, v171
	v_mul_f32_e32 v44, v44, v172
	v_mul_f32_e32 v45, v45, v173
	v_cvt_pk_bf16_f32 v158, v42, v43
	v_cvt_pk_bf16_f32 v159, v44, v45
	v_mul_f32_e32 v170, 0xbfb8aa3b, v46
	v_mul_f32_e32 v171, 0xbfb8aa3b, v47
	v_mul_f32_e32 v172, 0xbfb8aa3b, v48
	v_mul_f32_e32 v173, 0xbfb8aa3b, v49
	v_exp_f32_e32 v170, v170
	v_exp_f32_e32 v171, v171
	v_exp_f32_e32 v172, v172
	v_exp_f32_e32 v173, v173
	v_add_f32_e32 v170, 1.0, v170
	v_add_f32_e32 v171, 1.0, v171
	v_add_f32_e32 v172, 1.0, v172
	v_add_f32_e32 v173, 1.0, v173
	v_rcp_f32_e32 v170, v170
	v_rcp_f32_e32 v171, v171
	v_rcp_f32_e32 v172, v172
	v_rcp_f32_e32 v173, v173
	s_nop 0
	v_mul_f32_e32 v46, v46, v170
	v_mul_f32_e32 v47, v47, v171
	v_mul_f32_e32 v48, v48, v172
	v_mul_f32_e32 v49, v49, v173
	v_cvt_pk_bf16_f32 v160, v46, v47
	v_cvt_pk_bf16_f32 v161, v48, v49
	global_store_dwordx4 v148, v[158:161], s[8:9]
	s_add_u32 s8, s8, 0xf000
	s_addc_u32 s9, s9, 0
	s_waitcnt lgkmcnt(2)
	v_mul_f32_e32 v170, 0xbfb8aa3b, v50
	v_mul_f32_e32 v171, 0xbfb8aa3b, v51
	v_mul_f32_e32 v172, 0xbfb8aa3b, v52
	v_mul_f32_e32 v173, 0xbfb8aa3b, v53
	v_exp_f32_e32 v170, v170
	v_exp_f32_e32 v171, v171
	v_exp_f32_e32 v172, v172
	v_exp_f32_e32 v173, v173
	v_add_f32_e32 v170, 1.0, v170
	v_add_f32_e32 v171, 1.0, v171
	v_add_f32_e32 v172, 1.0, v172
	v_add_f32_e32 v173, 1.0, v173
	v_rcp_f32_e32 v170, v170
	v_rcp_f32_e32 v171, v171
	v_rcp_f32_e32 v172, v172
	v_rcp_f32_e32 v173, v173
	s_nop 0
	v_mul_f32_e32 v50, v50, v170
	v_mul_f32_e32 v51, v51, v171
	v_mul_f32_e32 v52, v52, v172
	v_mul_f32_e32 v53, v53, v173
	v_cvt_pk_bf16_f32 v162, v50, v51
	v_cvt_pk_bf16_f32 v163, v52, v53
	v_mul_f32_e32 v170, 0xbfb8aa3b, v54
	v_mul_f32_e32 v171, 0xbfb8aa3b, v55
	v_mul_f32_e32 v172, 0xbfb8aa3b, v56
	v_mul_f32_e32 v173, 0xbfb8aa3b, v57
	v_exp_f32_e32 v170, v170
	v_exp_f32_e32 v171, v171
	v_exp_f32_e32 v172, v172
	v_exp_f32_e32 v173, v173
	v_add_f32_e32 v170, 1.0, v170
	v_add_f32_e32 v171, 1.0, v171
	v_add_f32_e32 v172, 1.0, v172
	v_add_f32_e32 v173, 1.0, v173
	v_rcp_f32_e32 v170, v170
	v_rcp_f32_e32 v171, v171
	v_rcp_f32_e32 v172, v172
	v_rcp_f32_e32 v173, v173
	s_nop 0
	v_mul_f32_e32 v54, v54, v170
	v_mul_f32_e32 v55, v55, v171
	v_mul_f32_e32 v56, v56, v172
	v_mul_f32_e32 v57, v57, v173
	v_cvt_pk_bf16_f32 v164, v54, v55
	v_cvt_pk_bf16_f32 v165, v56, v57
	global_store_dwordx4 v148, v[162:165], s[8:9]
	s_add_u32 s8, s8, 0xf000
	s_addc_u32 s9, s9, 0
	s_waitcnt lgkmcnt(0)
	v_mul_f32_e32 v170, 0xbfb8aa3b, v58
	v_mul_f32_e32 v171, 0xbfb8aa3b, v59
	v_mul_f32_e32 v172, 0xbfb8aa3b, v60
	v_mul_f32_e32 v173, 0xbfb8aa3b, v61
	v_exp_f32_e32 v170, v170
	v_exp_f32_e32 v171, v171
	v_exp_f32_e32 v172, v172
	v_exp_f32_e32 v173, v173
	v_add_f32_e32 v170, 1.0, v170
	v_add_f32_e32 v171, 1.0, v171
	v_add_f32_e32 v172, 1.0, v172
	v_add_f32_e32 v173, 1.0, v173
	v_rcp_f32_e32 v170, v170
	v_rcp_f32_e32 v171, v171
	v_rcp_f32_e32 v172, v172
	v_rcp_f32_e32 v173, v173
	s_nop 0
	v_mul_f32_e32 v58, v58, v170
	v_mul_f32_e32 v59, v59, v171
	v_mul_f32_e32 v60, v60, v172
	v_mul_f32_e32 v61, v61, v173
	v_cvt_pk_bf16_f32 v166, v58, v59
	v_cvt_pk_bf16_f32 v167, v60, v61
	v_mul_f32_e32 v170, 0xbfb8aa3b, v62
	v_mul_f32_e32 v171, 0xbfb8aa3b, v63
	v_mul_f32_e32 v172, 0xbfb8aa3b, v64
	v_mul_f32_e32 v173, 0xbfb8aa3b, v65
	v_exp_f32_e32 v170, v170
	v_exp_f32_e32 v171, v171
	v_exp_f32_e32 v172, v172
	v_exp_f32_e32 v173, v173
	v_add_f32_e32 v170, 1.0, v170
	v_add_f32_e32 v171, 1.0, v171
	v_add_f32_e32 v172, 1.0, v172
	v_add_f32_e32 v173, 1.0, v173
	v_rcp_f32_e32 v170, v170
	v_rcp_f32_e32 v171, v171
	v_rcp_f32_e32 v172, v172
	v_rcp_f32_e32 v173, v173
	s_nop 0
	v_mul_f32_e32 v62, v62, v170
	v_mul_f32_e32 v63, v63, v171
	v_mul_f32_e32 v64, v64, v172
	v_mul_f32_e32 v65, v65, v173
	v_cvt_pk_bf16_f32 v168, v62, v63
	v_cvt_pk_bf16_f32 v169, v64, v65
	global_store_dwordx4 v148, v[166:169], s[8:9]
	s_add_u32 s8, s8, 0xf000
	s_addc_u32 s9, s9, 0
	ds_write2_b32 v146, v18, v2 offset0:0 offset1:32
	ds_write2_b32 v146, v19, v3 offset0:68 offset1:100
	ds_write2_b32 v146, v20, v4 offset0:136 offset1:168
	ds_write2_b32 v146, v21, v5 offset0:204 offset1:236
	v_add_u32_e32 v146, 0x880, v146
	ds_write2_b32 v146, v22, v6 offset0:0 offset1:32
	ds_write2_b32 v146, v23, v7 offset0:68 offset1:100
	ds_write2_b32 v146, v24, v8 offset0:136 offset1:168
	ds_write2_b32 v146, v25, v9 offset0:204 offset1:236
	v_add_u32_e32 v146, 0x880, v146
	ds_write2_b32 v146, v26, v10 offset0:0 offset1:32
	ds_write2_b32 v146, v27, v11 offset0:68 offset1:100
	ds_write2_b32 v146, v28, v12 offset0:136 offset1:168
	ds_write2_b32 v146, v29, v13 offset0:204 offset1:236
	v_add_u32_e32 v146, 0x880, v146
	ds_write2_b32 v146, v30, v14 offset0:0 offset1:32
	ds_write2_b32 v146, v31, v15 offset0:68 offset1:100
	ds_write2_b32 v146, v32, v16 offset0:136 offset1:168
	ds_write2_b32 v146, v33, v17 offset0:204 offset1:236
	v_subrev_u32_e32 v146, 0x1980, v146
	ds_read_b128 v[2:5], v147
	ds_read_b128 v[6:9], v147 offset:16
	ds_read_b128 v[10:13], v147 offset:2176
	ds_read_b128 v[14:17], v147 offset:2192
	ds_read_b128 v[18:21], v147 offset:4352
	ds_read_b128 v[22:25], v147 offset:4368
	ds_read_b128 v[26:29], v147 offset:6528
	ds_read_b128 v[30:33], v147 offset:6544
	s_waitcnt lgkmcnt(0)
	s_barrier
	v_mul_f32_e32 v170, 0xbfb8aa3b, v2
	v_mul_f32_e32 v171, 0xbfb8aa3b, v3
	v_mul_f32_e32 v172, 0xbfb8aa3b, v4
	v_mul_f32_e32 v173, 0xbfb8aa3b, v5
	v_exp_f32_e32 v170, v170
	v_exp_f32_e32 v171, v171
	v_exp_f32_e32 v172, v172
	v_exp_f32_e32 v173, v173
	v_add_f32_e32 v170, 1.0, v170
	v_add_f32_e32 v171, 1.0, v171
	v_add_f32_e32 v172, 1.0, v172
	v_add_f32_e32 v173, 1.0, v173
	v_rcp_f32_e32 v170, v170
	v_rcp_f32_e32 v171, v171
	v_rcp_f32_e32 v172, v172
	v_rcp_f32_e32 v173, v173
	s_nop 0
	v_mul_f32_e32 v2, v2, v170
	v_mul_f32_e32 v3, v3, v171
	v_mul_f32_e32 v4, v4, v172
	v_mul_f32_e32 v5, v5, v173
	v_cvt_pk_bf16_f32 v154, v2, v3
	v_cvt_pk_bf16_f32 v155, v4, v5
	v_mul_f32_e32 v170, 0xbfb8aa3b, v6
	v_mul_f32_e32 v171, 0xbfb8aa3b, v7
	v_mul_f32_e32 v172, 0xbfb8aa3b, v8
	v_mul_f32_e32 v173, 0xbfb8aa3b, v9
	v_exp_f32_e32 v170, v170
	v_exp_f32_e32 v171, v171
	v_exp_f32_e32 v172, v172
	v_exp_f32_e32 v173, v173
	v_add_f32_e32 v170, 1.0, v170
	v_add_f32_e32 v171, 1.0, v171
	v_add_f32_e32 v172, 1.0, v172
	v_add_f32_e32 v173, 1.0, v173
	v_rcp_f32_e32 v170, v170
	v_rcp_f32_e32 v171, v171
	v_rcp_f32_e32 v172, v172
	v_rcp_f32_e32 v173, v173
	s_nop 0
	v_mul_f32_e32 v6, v6, v170
	v_mul_f32_e32 v7, v7, v171
	v_mul_f32_e32 v8, v8, v172
	v_mul_f32_e32 v9, v9, v173
	v_cvt_pk_bf16_f32 v156, v6, v7
	v_cvt_pk_bf16_f32 v157, v8, v9
	global_store_dwordx4 v148, v[154:157], s[8:9]
	s_add_u32 s8, s8, 0xf000
	s_addc_u32 s9, s9, 0
	v_mul_f32_e32 v170, 0xbfb8aa3b, v10
	v_mul_f32_e32 v171, 0xbfb8aa3b, v11
	v_mul_f32_e32 v172, 0xbfb8aa3b, v12
	v_mul_f32_e32 v173, 0xbfb8aa3b, v13
	v_exp_f32_e32 v170, v170
	v_exp_f32_e32 v171, v171
	v_exp_f32_e32 v172, v172
	v_exp_f32_e32 v173, v173
	v_add_f32_e32 v170, 1.0, v170
	v_add_f32_e32 v171, 1.0, v171
	v_add_f32_e32 v172, 1.0, v172
	v_add_f32_e32 v173, 1.0, v173
	v_rcp_f32_e32 v170, v170
	v_rcp_f32_e32 v171, v171
	v_rcp_f32_e32 v172, v172
	v_rcp_f32_e32 v173, v173
	s_nop 0
	v_mul_f32_e32 v10, v10, v170
	v_mul_f32_e32 v11, v11, v171
	v_mul_f32_e32 v12, v12, v172
	v_mul_f32_e32 v13, v13, v173
	v_cvt_pk_bf16_f32 v158, v10, v11
	v_cvt_pk_bf16_f32 v159, v12, v13
	v_mul_f32_e32 v170, 0xbfb8aa3b, v14
	v_mul_f32_e32 v171, 0xbfb8aa3b, v15
	v_mul_f32_e32 v172, 0xbfb8aa3b, v16
	v_mul_f32_e32 v173, 0xbfb8aa3b, v17
	v_exp_f32_e32 v170, v170
	v_exp_f32_e32 v171, v171
	v_exp_f32_e32 v172, v172
	v_exp_f32_e32 v173, v173
	v_add_f32_e32 v170, 1.0, v170
	v_add_f32_e32 v171, 1.0, v171
	v_add_f32_e32 v172, 1.0, v172
	v_add_f32_e32 v173, 1.0, v173
	v_rcp_f32_e32 v170, v170
	v_rcp_f32_e32 v171, v171
	v_rcp_f32_e32 v172, v172
	v_rcp_f32_e32 v173, v173
	s_nop 0
	v_mul_f32_e32 v14, v14, v170
	v_mul_f32_e32 v15, v15, v171
	v_mul_f32_e32 v16, v16, v172
	v_mul_f32_e32 v17, v17, v173
	v_cvt_pk_bf16_f32 v160, v14, v15
	v_cvt_pk_bf16_f32 v161, v16, v17
	global_store_dwordx4 v148, v[158:161], s[8:9]
	s_add_u32 s8, s8, 0xf000
	s_addc_u32 s9, s9, 0
	v_mul_f32_e32 v170, 0xbfb8aa3b, v18
	v_mul_f32_e32 v171, 0xbfb8aa3b, v19
	v_mul_f32_e32 v172, 0xbfb8aa3b, v20
	v_mul_f32_e32 v173, 0xbfb8aa3b, v21
	v_exp_f32_e32 v170, v170
	v_exp_f32_e32 v171, v171
	v_exp_f32_e32 v172, v172
	v_exp_f32_e32 v173, v173
	v_add_f32_e32 v170, 1.0, v170
	v_add_f32_e32 v171, 1.0, v171
	v_add_f32_e32 v172, 1.0, v172
	v_add_f32_e32 v173, 1.0, v173
	v_rcp_f32_e32 v170, v170
	v_rcp_f32_e32 v171, v171
	v_rcp_f32_e32 v172, v172
	v_rcp_f32_e32 v173, v173
	s_nop 0
	v_mul_f32_e32 v18, v18, v170
	v_mul_f32_e32 v19, v19, v171
	v_mul_f32_e32 v20, v20, v172
	v_mul_f32_e32 v21, v21, v173
	v_cvt_pk_bf16_f32 v162, v18, v19
	v_cvt_pk_bf16_f32 v163, v20, v21
	v_mul_f32_e32 v170, 0xbfb8aa3b, v22
	v_mul_f32_e32 v171, 0xbfb8aa3b, v23
	v_mul_f32_e32 v172, 0xbfb8aa3b, v24
	v_mul_f32_e32 v173, 0xbfb8aa3b, v25
	v_exp_f32_e32 v170, v170
	v_exp_f32_e32 v171, v171
	v_exp_f32_e32 v172, v172
	v_exp_f32_e32 v173, v173
	v_add_f32_e32 v170, 1.0, v170
	v_add_f32_e32 v171, 1.0, v171
	v_add_f32_e32 v172, 1.0, v172
	v_add_f32_e32 v173, 1.0, v173
	v_rcp_f32_e32 v170, v170
	v_rcp_f32_e32 v171, v171
	v_rcp_f32_e32 v172, v172
	v_rcp_f32_e32 v173, v173
	s_nop 0
	v_mul_f32_e32 v22, v22, v170
	v_mul_f32_e32 v23, v23, v171
	v_mul_f32_e32 v24, v24, v172
	v_mul_f32_e32 v25, v25, v173
	v_cvt_pk_bf16_f32 v164, v22, v23
	v_cvt_pk_bf16_f32 v165, v24, v25
	global_store_dwordx4 v148, v[162:165], s[8:9]
	s_add_u32 s8, s8, 0xf000
	s_addc_u32 s9, s9, 0
	v_mul_f32_e32 v170, 0xbfb8aa3b, v26
	v_mul_f32_e32 v171, 0xbfb8aa3b, v27
	v_mul_f32_e32 v172, 0xbfb8aa3b, v28
	v_mul_f32_e32 v173, 0xbfb8aa3b, v29
	v_exp_f32_e32 v170, v170
	v_exp_f32_e32 v171, v171
	v_exp_f32_e32 v172, v172
	v_exp_f32_e32 v173, v173
	v_add_f32_e32 v170, 1.0, v170
	v_add_f32_e32 v171, 1.0, v171
	v_add_f32_e32 v172, 1.0, v172
	v_add_f32_e32 v173, 1.0, v173
	v_rcp_f32_e32 v170, v170
	v_rcp_f32_e32 v171, v171
	v_rcp_f32_e32 v172, v172
	v_rcp_f32_e32 v173, v173
	s_nop 0
	v_mul_f32_e32 v26, v26, v170
	v_mul_f32_e32 v27, v27, v171
	v_mul_f32_e32 v28, v28, v172
	v_mul_f32_e32 v29, v29, v173
	v_cvt_pk_bf16_f32 v166, v26, v27
	v_cvt_pk_bf16_f32 v167, v28, v29
	v_mul_f32_e32 v170, 0xbfb8aa3b, v30
	v_mul_f32_e32 v171, 0xbfb8aa3b, v31
	v_mul_f32_e32 v172, 0xbfb8aa3b, v32
	v_mul_f32_e32 v173, 0xbfb8aa3b, v33
	v_exp_f32_e32 v170, v170
	v_exp_f32_e32 v171, v171
	v_exp_f32_e32 v172, v172
	v_exp_f32_e32 v173, v173
	v_add_f32_e32 v170, 1.0, v170
	v_add_f32_e32 v171, 1.0, v171
	v_add_f32_e32 v172, 1.0, v172
	v_add_f32_e32 v173, 1.0, v173
	v_rcp_f32_e32 v170, v170
	v_rcp_f32_e32 v171, v171
	v_rcp_f32_e32 v172, v172
	v_rcp_f32_e32 v173, v173
	s_nop 0
	v_mul_f32_e32 v30, v30, v170
	v_mul_f32_e32 v31, v31, v171
	v_mul_f32_e32 v32, v32, v172
	v_mul_f32_e32 v33, v33, v173
	v_cvt_pk_bf16_f32 v168, v30, v31
	v_cvt_pk_bf16_f32 v169, v32, v33
	global_store_dwordx4 v148, v[166:169], s[8:9]
	s_add_u32 s8, s8, 0xf000
	s_addc_u32 s9, s9, 0
	s_add_i32 s70, s70, s10
	s_setprio 0
	s_cmp_lt_i32 s70, s71
	s_cbranch_scc0 .LBB0_209
	s_branch .LBB0_215
